# scan loaders: previous chunk's y reduction moved ahead of the operand staging writes
# speedup vs baseline: 1.0151x; 1.0151x over previous
.LBB0_791:
	s_andn2_saveexec_b64 s[36:37], s[36:37]
	s_cbranch_execz .LBB0_786
	s_cmp_eq_u32 s34, 0
	s_cbranch_scc1 .Lyred_first
	s_and_b32 s0, s31, 0x1000
	v_lshl_add_u32 v44, s0, 2, v125
	ds_read_b128 v[28:31], v44
	ds_read_b128 v[36:39], v44 offset:16
	ds_read_b128 v[40:43], v44 offset:32
	ds_read_b128 v[44:47], v44 offset:48
	s_waitcnt lgkmcnt(2)
	v_pk_add_f32 v[30:31], v[30:31], v[38:39]
	v_pk_add_f32 v[28:29], v[28:29], v[36:37]
	s_waitcnt lgkmcnt(0)
	v_pk_add_f32 v[36:37], v[42:43], v[46:47]
	v_pk_add_f32 v[38:39], v[40:41], v[44:45]
	v_pk_add_f32 v[30:31], v[30:31], v[36:37]
	v_pk_add_f32 v[28:29], v[28:29], v[38:39]
	s_nop 0
	v_pk_mov_b32 v[36:37], v[28:29], v[30:31] op_sel:[1,0]
	v_mov_b32_e32 v29, v31
	v_pk_add_f32 v[28:29], v[36:37], v[28:29]
	s_nop 0
	v_add_f32_e32 v30, v28, v29
	v_cmp_lt_i32_e32 vcc, -1, v126
	s_and_saveexec_b64 s[44:45], vcc
	v_mad_u64_u32 v[28:29], s[0:1], v126, s62, v[90:91]
	global_store_dword v[28:29], v30, off
	s_or_b64 exec, exec, s[44:45]
.Lyred_first:
	s_cmp_eq_u32 s34, 0x379000
	s_cbranch_scc1 .LBB0_823
	s_andn2_b32 s0, 1, s54
	s_mul_i32 s0, s0, 0xc000
	s_add_i32 s4, s0, 0
	v_add_u32_e32 v28, s4, v103
	s_and_saveexec_b64 s[0:1], s[10:11]
	s_xor_b64 s[44:45], exec, s[0:1]
	s_cbranch_execz .LBB0_795
	v_lshl_add_u32 v28, v104, 2, v28
	v_add3_u32 v36, v28, v127, s53
	s_waitcnt vmcnt(6)
	s_mov_b32 vcc_lo, 0xaaaaaaaa
	s_mov_b32 vcc_hi, 0xaaaaaaaa
	v_cndmask_b32_e32 v37, v2, v0, vcc
	v_cndmask_b32_e32 v38, v3, v1, vcc
	v_add_u32_e32 v40, -16, v36
	v_cndmask_b32_e32 v36, v36, v40, vcc
	v_mov_b32_dpp v41, v37 quad_perm:[1,0,3,2] row_mask:0xf bank_mask:0xf bound_ctrl:1
	v_mov_b32_dpp v42, v38 quad_perm:[1,0,3,2] row_mask:0xf bank_mask:0xf bound_ctrl:1
	v_cndmask_b32_e32 v37, v0, v41, vcc
	v_cndmask_b32_e32 v38, v1, v42, vcc
	v_cndmask_b32_e32 v41, v41, v2, vcc
	v_cndmask_b32_e32 v42, v42, v3, vcc
	v_lshlrev_b32_e32 v28, 16, v37
	v_and_b32_e32 v29, 0xffff0000, v37
	v_lshlrev_b32_e32 v30, 16, v38
	v_and_b32_e32 v31, 0xffff0000, v38
	ds_write_b128 v36, v[28:31]
	v_lshlrev_b32_e32 v28, 16, v41
	v_and_b32_e32 v29, 0xffff0000, v41
	v_lshlrev_b32_e32 v30, 16, v42
	v_and_b32_e32 v31, 0xffff0000, v42
	ds_write_b128 v36, v[28:31] offset:32

.LBB0_824:
	s_waitcnt vmcnt(0)
	v_lshl_add_u64 v[24:25], v[92:93], 0, s[34:35]
	v_add_co_u32_e32 v0, vcc, 0x16bfe000, v24
	s_nop 1
	v_addc_co_u32_e32 v1, vcc, 0, v25, vcc
	v_add_co_u32_e32 v4, vcc, 0x16bff000, v24
	s_nop 1
	v_addc_co_u32_e32 v5, vcc, 0, v25, vcc
	v_add_co_u32_e32 v8, vcc, 0x16c00000, v24
	global_load_dwordx4 v[0:3], v[0:1], off
	s_nop 0
	global_load_dwordx4 v[4:7], v[4:5], off
	v_addc_co_u32_e32 v9, vcc, 0, v25, vcc
	v_add_co_u32_e32 v12, vcc, 0x16c01000, v24
	s_nop 1
	v_addc_co_u32_e32 v13, vcc, 0, v25, vcc
	v_add_co_u32_e32 v16, vcc, 0x16c02000, v24
	global_load_dwordx4 v[8:11], v[8:9], off
	s_nop 0
	global_load_dwordx4 v[12:15], v[12:13], off
	v_addc_co_u32_e32 v17, vcc, 0, v25, vcc
	v_add_co_u32_e32 v20, vcc, 0x16c03000, v24
	s_nop 1
	v_addc_co_u32_e32 v21, vcc, 0, v25, vcc
	v_add_co_u32_e32 v24, vcc, 0x16c04000, v24
	global_load_dwordx4 v[16:19], v[16:17], off
	s_nop 0
	global_load_dwordx4 v[20:23], v[20:21], off
	v_addc_co_u32_e32 v25, vcc, 0, v25, vcc
	global_load_dwordx4 v[24:27], v[24:25], off
	s_cmp_eq_u32 s34, 0
	s_cbranch_scc1 .LBB0_786
.LBB0_825:
	s_branch .LBB0_786
.LBB0_826:
	s_and_saveexec_b64 s[8:9], s[26:27]
	s_cbranch_execz .Lscan_epi_done
	v_mov_b32_e32 v12, v102
	v_pk_fma_f32 v[4:5], v[60:61], v[64:65], v[56:57] op_sel_hi:[0,1,1]
	v_pk_fma_f32 v[6:7], v[60:61], v[66:67], v[58:59] op_sel_hi:[0,1,1]
	v_pk_mul_f32 v[80:81], v[4:5], v[80:81]
	v_pk_fma_f32 v[80:81], v[6:7], v[82:83], v[80:81]
	v_add_f32_e32 v80, v80, v81
	v_pk_mul_f32 v[76:77], v[76:77], v[2:3] op_sel_hi:[1,0]
	v_pk_mul_f32 v[78:79], v[78:79], v[2:3] op_sel_hi:[1,0]
	v_add_f32_dpp v80, v80, v80 quad_perm:[1,0,3,2] row_mask:0xf bank_mask:0xf bound_ctrl:1
	v_pk_fma_f32 v[76:77], v[4:5], v[68:69], v[76:77]
	v_pk_fma_f32 v[78:79], v[6:7], v[70:71], v[78:79]
	v_add_f32_dpp v80, v80, v80 quad_perm:[2,3,0,1] row_mask:0xf bank_mask:0xf bound_ctrl:1
	v_pk_mul_f32 v[52:53], v[52:53], v[4:5]
	v_pk_fma_f32 v[52:53], v[6:7], v[54:55], v[52:53]
	v_add_f32_dpp v80, v80, v80 row_half_mirror row_mask:0xf bank_mask:0xf bound_ctrl:1
	v_add_f32_e32 v9, v52, v53
	s_nop 0
	v_add_f32_dpp v80, v80, v80 row_mirror row_mask:0xf bank_mask:0xf bound_ctrl:1
	v_pk_fma_f32 v[4:5], v[80:81], v[84:85], v[76:77] op_sel_hi:[0,1,1]
	v_pk_fma_f32 v[6:7], v[80:81], v[86:87], v[78:79] op_sel_hi:[0,1,1]
	v_pk_mul_f32 v[116:117], v[4:5], v[116:117]
	v_pk_fma_f32 v[116:117], v[6:7], v[118:119], v[116:117]
	v_add_f32_e32 v116, v116, v117
	v_pk_mul_f32 v[112:113], v[112:113], v[2:3] op_sel:[0,1] op_sel_hi:[1,1]
	v_pk_mul_f32 v[114:115], v[114:115], v[2:3] op_sel:[0,1] op_sel_hi:[1,1]
	v_add_f32_dpp v116, v116, v116 quad_perm:[1,0,3,2] row_mask:0xf bank_mask:0xf bound_ctrl:1
	v_pk_fma_f32 v[112:113], v[4:5], v[104:105], v[112:113]
	v_pk_fma_f32 v[114:115], v[6:7], v[106:107], v[114:115]
	v_add_f32_dpp v116, v116, v116 quad_perm:[2,3,0,1] row_mask:0xf bank_mask:0xf bound_ctrl:1
	v_pk_mul_f32 v[72:73], v[72:73], v[4:5]
	v_pk_fma_f32 v[72:73], v[6:7], v[74:75], v[72:73]
	v_add_f32_dpp v116, v116, v116 row_half_mirror row_mask:0xf bank_mask:0xf bound_ctrl:1
	v_add_f32_e32 v8, v72, v73
	ds_write2st64_b32 v12, v9, v8 offset0:0 offset1:2
	s_nop 0
	v_add_f32_dpp v116, v116, v116 row_mirror row_mask:0xf bank_mask:0xf bound_ctrl:1
	v_pk_fma_f32 v[4:5], v[116:117], v[120:121], v[112:113] op_sel_hi:[0,1,1]
	v_pk_fma_f32 v[6:7], v[116:117], v[122:123], v[114:115] op_sel_hi:[0,1,1]
	v_pk_mul_f32 v[108:109], v[108:109], v[4:5]
	v_pk_fma_f32 v[108:109], v[6:7], v[110:111], v[108:109]
	v_add_f32_e32 v9, v108, v109
	ds_write_b32 v12, v9 offset:1024
	s_nop 0
